# MLA kv up-projection epilogue: eight RS loads issued together; 7 load+vmcnt(0) pairs that drained the previous group's stores removed
# baseline (speedup 1.0000x reference)
.LBB0_833:
	ds_read_b128 v[148:151], v166
	ds_read_b128 v[152:155], v166 offset:1024
	ds_read_b128 v[156:159], v166 offset:2048
	ds_read_b128 v[160:163], v166 offset:3072
	s_add_u32 s2, s8, 0xfff80080
	s_addc_u32 s3, s9, -1
	s_cmp_eq_u32 s27, 2
	s_cselect_b32 s3, s29, s3
	s_cselect_b32 s2, s44, s2
	s_cselect_b32 s11, s0, s5
	s_cselect_b32 s10, s1, s4
	v_lshl_add_u64 v[174:175], s[8:9], 0, v[142:143]
	s_add_i32 m0, s55, 0xc000
	ds_read_b128 v[180:183], v167
	ds_read_b128 v[184:187], v167 offset:1024
	ds_read_b128 v[188:191], v167 offset:2048
	ds_read_b128 v[192:195], v167 offset:3072
	ds_read_b128 v[196:199], v167 offset:4096
	ds_read_b128 v[200:203], v167 offset:5120
	ds_read_b128 v[204:207], v167 offset:6144
	ds_read_b128 v[208:211], v167 offset:7168
	global_load_lds_dwordx4 v[174:175], off
	v_lshl_add_u64 v[174:175], s[8:9], 0, v[144:145]
	s_add_i32 m0, s55, 0xe000
	s_nop 0
	global_load_lds_dwordx4 v[174:175], off
	s_waitcnt lgkmcnt(8)
	s_barrier
	s_waitcnt lgkmcnt(0)
	s_setprio 1
	s_waitcnt lgkmcnt(0)
	v_mfma_f32_16x16x32_bf16 v[124:127], v[148:151], v[180:183], v[124:127]
	v_mfma_f32_16x16x32_bf16 v[120:123], v[156:159], v[180:183], v[120:123]
	v_mfma_f32_16x16x32_bf16 v[108:111], v[148:151], v[188:191], v[108:111]
	v_mfma_f32_16x16x32_bf16 v[104:107], v[156:159], v[188:191], v[104:107]
	v_mfma_f32_16x16x32_bf16 v[92:95], v[148:151], v[196:199], v[92:95]
	v_mfma_f32_16x16x32_bf16 v[88:91], v[156:159], v[196:199], v[88:91]
	v_mfma_f32_16x16x32_bf16 v[76:79], v[148:151], v[204:207], v[76:79]
	v_mfma_f32_16x16x32_bf16 v[72:75], v[156:159], v[204:207], v[72:75]
	v_mfma_f32_16x16x32_bf16 v[124:127], v[152:155], v[184:187], v[124:127]
	v_mfma_f32_16x16x32_bf16 v[120:123], v[160:163], v[184:187], v[120:123]
	v_mfma_f32_16x16x32_bf16 v[108:111], v[152:155], v[192:195], v[108:111]
	v_mfma_f32_16x16x32_bf16 v[104:107], v[160:163], v[192:195], v[104:107]
	v_mfma_f32_16x16x32_bf16 v[92:95], v[152:155], v[200:203], v[92:95]
	v_mfma_f32_16x16x32_bf16 v[88:91], v[160:163], v[200:203], v[88:91]
	v_mfma_f32_16x16x32_bf16 v[76:79], v[152:155], v[208:211], v[76:79]
	v_mfma_f32_16x16x32_bf16 v[72:75], v[160:163], v[208:211], v[72:75]
	s_setprio 0
	s_barrier
	s_add_i32 s45, s65, s54
	v_lshl_add_u64 v[174:175], s[10:11], 0, v[128:129]
	s_mov_b32 m0, s45
	ds_read_b128 v[212:215], v168
	ds_read_b128 v[216:219], v168 offset:1024
	ds_read_b128 v[220:223], v168 offset:2048
	ds_read_b128 v[224:227], v168 offset:3072
	global_load_lds_dwordx4 v[174:175], off
	v_lshl_add_u64 v[228:229], s[10:11], 0, v[130:131]
	s_add_i32 m0, s45, 0x2000
	s_nop 0
	global_load_lds_dwordx4 v[228:229], off
	s_barrier
	s_waitcnt lgkmcnt(0)
	s_setprio 1
	s_waitcnt lgkmcnt(0)
	v_mfma_f32_16x16x32_bf16 v[116:119], v[212:215], v[180:183], v[116:119]
	v_mfma_f32_16x16x32_bf16 v[112:115], v[220:223], v[180:183], v[112:115]
	v_mfma_f32_16x16x32_bf16 v[100:103], v[212:215], v[188:191], v[100:103]
	v_mfma_f32_16x16x32_bf16 v[96:99], v[220:223], v[188:191], v[96:99]
	v_mfma_f32_16x16x32_bf16 v[84:87], v[212:215], v[196:199], v[84:87]
	v_mfma_f32_16x16x32_bf16 v[80:83], v[220:223], v[196:199], v[80:83]
	v_mfma_f32_16x16x32_bf16 v[68:71], v[212:215], v[204:207], v[68:71]
	v_mfma_f32_16x16x32_bf16 v[64:67], v[220:223], v[204:207], v[64:67]
	v_mfma_f32_16x16x32_bf16 v[116:119], v[216:219], v[184:187], v[116:119]
	v_mfma_f32_16x16x32_bf16 v[112:115], v[224:227], v[184:187], v[112:115]
	v_mfma_f32_16x16x32_bf16 v[100:103], v[216:219], v[192:195], v[100:103]
	v_mfma_f32_16x16x32_bf16 v[96:99], v[224:227], v[192:195], v[96:99]
	v_mfma_f32_16x16x32_bf16 v[84:87], v[216:219], v[200:203], v[84:87]
	v_mfma_f32_16x16x32_bf16 v[80:83], v[224:227], v[200:203], v[80:83]
	v_mfma_f32_16x16x32_bf16 v[68:71], v[216:219], v[208:211], v[68:71]
	v_mfma_f32_16x16x32_bf16 v[64:67], v[224:227], v[208:211], v[64:67]
	s_setprio 0
	s_mov_b32 m0, s55
	v_lshl_add_u64 v[230:231], s[2:3], 0, v[128:129]
	s_barrier
	ds_read_b128 v[180:183], v167 offset:16384
	ds_read_b128 v[184:187], v167 offset:17408
	ds_read_b128 v[188:191], v167 offset:18432
	ds_read_b128 v[192:195], v167 offset:19456
	ds_read_b128 v[196:199], v167 offset:20480
	ds_read_b128 v[200:203], v167 offset:21504
	ds_read_b128 v[204:207], v167 offset:22528
	ds_read_b128 v[208:211], v167 offset:23552
	global_load_lds_dwordx4 v[230:231], off
	v_lshl_add_u64 v[232:233], s[2:3], 0, v[130:131]
	s_mov_b32 m0, s56
	s_nop 0
	global_load_lds_dwordx4 v[232:233], off
	s_barrier
	s_waitcnt lgkmcnt(0)
	s_setprio 1
	s_waitcnt lgkmcnt(0)
	v_mfma_f32_16x16x32_bf16 v[60:63], v[148:151], v[180:183], v[60:63]
	v_mfma_f32_16x16x32_bf16 v[56:59], v[156:159], v[180:183], v[56:59]
	v_mfma_f32_16x16x32_bf16 v[44:47], v[148:151], v[188:191], v[44:47]
	v_mfma_f32_16x16x32_bf16 v[40:43], v[156:159], v[188:191], v[40:43]
	v_mfma_f32_16x16x32_bf16 v[28:31], v[148:151], v[196:199], v[28:31]
	v_mfma_f32_16x16x32_bf16 v[24:27], v[156:159], v[196:199], v[24:27]
	v_mfma_f32_16x16x32_bf16 v[12:15], v[148:151], v[204:207], v[12:15]
	v_mfma_f32_16x16x32_bf16 v[8:11], v[156:159], v[204:207], v[8:11]
	v_mfma_f32_16x16x32_bf16 v[60:63], v[152:155], v[184:187], v[60:63]
	v_mfma_f32_16x16x32_bf16 v[56:59], v[160:163], v[184:187], v[56:59]
	v_mfma_f32_16x16x32_bf16 v[44:47], v[152:155], v[192:195], v[44:47]
	v_mfma_f32_16x16x32_bf16 v[40:43], v[160:163], v[192:195], v[40:43]
	v_mfma_f32_16x16x32_bf16 v[28:31], v[152:155], v[200:203], v[28:31]
	v_mfma_f32_16x16x32_bf16 v[24:27], v[160:163], v[200:203], v[24:27]
	v_mfma_f32_16x16x32_bf16 v[12:15], v[152:155], v[208:211], v[12:15]
	v_mfma_f32_16x16x32_bf16 v[8:11], v[160:163], v[208:211], v[8:11]
	s_setprio 0
	s_barrier
	s_add_u32 s46, s10, 0x80000
	s_addc_u32 s47, s11, 0
	s_add_i32 s45, s66, s54
	v_lshl_add_u64 v[148:149], s[46:47], 0, v[128:129]
	s_mov_b32 m0, s45
	s_nop 0
	global_load_lds_dwordx4 v[148:149], off
	v_lshl_add_u64 v[148:149], s[46:47], 0, v[130:131]
	s_add_i32 m0, s45, 0x2000
	s_nop 0
	global_load_lds_dwordx4 v[148:149], off
	s_waitcnt vmcnt(6)
	s_barrier
	s_setprio 1
	v_mfma_f32_16x16x32_bf16 v[52:55], v[212:215], v[180:183], v[52:55]
	v_mfma_f32_16x16x32_bf16 v[48:51], v[220:223], v[180:183], v[48:51]
	v_mfma_f32_16x16x32_bf16 v[36:39], v[212:215], v[188:191], v[36:39]
	v_mfma_f32_16x16x32_bf16 v[32:35], v[220:223], v[188:191], v[32:35]
	v_mfma_f32_16x16x32_bf16 v[20:23], v[212:215], v[196:199], v[20:23]
	v_mfma_f32_16x16x32_bf16 v[16:19], v[220:223], v[196:199], v[16:19]
	v_mfma_f32_16x16x32_bf16 v[4:7], v[212:215], v[204:207], v[4:7]
	v_mfma_f32_16x16x32_bf16 v[0:3], v[220:223], v[204:207], v[0:3]
	v_mfma_f32_16x16x32_bf16 v[52:55], v[216:219], v[184:187], v[52:55]
	v_mfma_f32_16x16x32_bf16 v[48:51], v[224:227], v[184:187], v[48:51]
	v_mfma_f32_16x16x32_bf16 v[36:39], v[216:219], v[192:195], v[36:39]
	v_mfma_f32_16x16x32_bf16 v[32:35], v[224:227], v[192:195], v[32:35]
	v_mfma_f32_16x16x32_bf16 v[20:23], v[216:219], v[200:203], v[20:23]
	v_mfma_f32_16x16x32_bf16 v[16:19], v[224:227], v[200:203], v[16:19]
	v_mfma_f32_16x16x32_bf16 v[4:7], v[216:219], v[208:211], v[4:7]
	v_mfma_f32_16x16x32_bf16 v[0:3], v[224:227], v[208:211], v[0:3]
	s_setprio 0
	s_add_i32 s45, 0, 0x18000
	v_add_u32_e32 v132, s45, v165
	s_barrier
	ds_read_b128 v[148:151], v132
	ds_read_b128 v[152:155], v132 offset:1024
	ds_read_b128 v[156:159], v132 offset:2048
	ds_read_b128 v[160:163], v132 offset:3072
	s_add_u32 s2, s2, 0x80000
	s_addc_u32 s3, s3, 0
	s_mov_b32 m0, s57
	v_lshl_add_u64 v[212:213], s[2:3], 0, v[128:129]
	ds_read_b128 v[180:183], v167 offset:32768
	ds_read_b128 v[184:187], v167 offset:33792
	ds_read_b128 v[188:191], v167 offset:34816
	ds_read_b128 v[192:195], v167 offset:35840
	ds_read_b128 v[196:199], v167 offset:36864
	ds_read_b128 v[200:203], v167 offset:37888
	ds_read_b128 v[204:207], v167 offset:38912
	ds_read_b128 v[208:211], v167 offset:39936
	global_load_lds_dwordx4 v[212:213], off
	v_lshl_add_u64 v[212:213], s[2:3], 0, v[130:131]
	s_mov_b32 m0, s58
	s_nop 0
	global_load_lds_dwordx4 v[212:213], off
	s_waitcnt lgkmcnt(8)
	s_barrier
	s_waitcnt lgkmcnt(0)
	s_setprio 1
	s_waitcnt lgkmcnt(0)
	v_mfma_f32_16x16x32_bf16 v[124:127], v[148:151], v[180:183], v[124:127]
	v_mfma_f32_16x16x32_bf16 v[120:123], v[156:159], v[180:183], v[120:123]
	v_mfma_f32_16x16x32_bf16 v[108:111], v[148:151], v[188:191], v[108:111]
	v_mfma_f32_16x16x32_bf16 v[104:107], v[156:159], v[188:191], v[104:107]
	v_mfma_f32_16x16x32_bf16 v[92:95], v[148:151], v[196:199], v[92:95]
	v_mfma_f32_16x16x32_bf16 v[88:91], v[156:159], v[196:199], v[88:91]
	v_mfma_f32_16x16x32_bf16 v[76:79], v[148:151], v[204:207], v[76:79]
	v_mfma_f32_16x16x32_bf16 v[72:75], v[156:159], v[204:207], v[72:75]
	v_mfma_f32_16x16x32_bf16 v[124:127], v[152:155], v[184:187], v[124:127]
	v_mfma_f32_16x16x32_bf16 v[120:123], v[160:163], v[184:187], v[120:123]
	v_mfma_f32_16x16x32_bf16 v[108:111], v[152:155], v[192:195], v[108:111]
	v_mfma_f32_16x16x32_bf16 v[104:107], v[160:163], v[192:195], v[104:107]
	v_mfma_f32_16x16x32_bf16 v[92:95], v[152:155], v[200:203], v[92:95]
	v_mfma_f32_16x16x32_bf16 v[88:91], v[160:163], v[200:203], v[88:91]
	v_mfma_f32_16x16x32_bf16 v[76:79], v[152:155], v[208:211], v[76:79]
	v_mfma_f32_16x16x32_bf16 v[72:75], v[160:163], v[208:211], v[72:75]
	s_setprio 0
	s_barrier
	s_add_i32 s46, 0, 0x1c000
	s_add_i32 s2, s45, s54
	v_add_u32_e32 v132, s46, v165
	v_lshl_add_u64 v[174:175], v[174:175], 0, s[36:37]
	s_mov_b32 m0, s2
	ds_read_b128 v[212:215], v132
	ds_read_b128 v[216:219], v132 offset:1024
	ds_read_b128 v[220:223], v132 offset:2048
	ds_read_b128 v[224:227], v132 offset:3072
	global_load_lds_dwordx4 v[174:175], off
	v_lshl_add_u64 v[174:175], v[228:229], 0, s[36:37]
	s_add_i32 m0, s2, 0x2000
	s_nop 0
	global_load_lds_dwordx4 v[174:175], off
	s_barrier
	s_waitcnt lgkmcnt(0)
	s_setprio 1
	s_waitcnt lgkmcnt(0)
	v_mfma_f32_16x16x32_bf16 v[116:119], v[212:215], v[180:183], v[116:119]
	v_mfma_f32_16x16x32_bf16 v[112:115], v[220:223], v[180:183], v[112:115]
	v_mfma_f32_16x16x32_bf16 v[100:103], v[212:215], v[188:191], v[100:103]
	v_mfma_f32_16x16x32_bf16 v[96:99], v[220:223], v[188:191], v[96:99]
	v_mfma_f32_16x16x32_bf16 v[84:87], v[212:215], v[196:199], v[84:87]
	v_mfma_f32_16x16x32_bf16 v[80:83], v[220:223], v[196:199], v[80:83]
	v_mfma_f32_16x16x32_bf16 v[68:71], v[212:215], v[204:207], v[68:71]
	v_mfma_f32_16x16x32_bf16 v[64:67], v[220:223], v[204:207], v[64:67]
	v_mfma_f32_16x16x32_bf16 v[116:119], v[216:219], v[184:187], v[116:119]
	v_mfma_f32_16x16x32_bf16 v[112:115], v[224:227], v[184:187], v[112:115]
	v_mfma_f32_16x16x32_bf16 v[100:103], v[216:219], v[192:195], v[100:103]
	v_mfma_f32_16x16x32_bf16 v[96:99], v[224:227], v[192:195], v[96:99]
	v_mfma_f32_16x16x32_bf16 v[84:87], v[216:219], v[200:203], v[84:87]
	v_mfma_f32_16x16x32_bf16 v[80:83], v[224:227], v[200:203], v[80:83]
	v_mfma_f32_16x16x32_bf16 v[68:71], v[216:219], v[208:211], v[68:71]
	v_mfma_f32_16x16x32_bf16 v[64:67], v[224:227], v[208:211], v[64:67]
	s_setprio 0
	s_mov_b32 m0, s61
	v_lshl_add_u64 v[174:175], v[230:231], 0, s[36:37]
	s_barrier
	ds_read_b128 v[180:183], v167 offset:49152
	ds_read_b128 v[184:187], v167 offset:50176
	ds_read_b128 v[188:191], v167 offset:51200
	ds_read_b128 v[192:195], v167 offset:52224
	ds_read_b128 v[196:199], v167 offset:53248
	ds_read_b128 v[200:203], v167 offset:54272
	ds_read_b128 v[204:207], v167 offset:55296
	ds_read_b128 v[208:211], v167 offset:56320
	global_load_lds_dwordx4 v[174:175], off
	v_lshl_add_u64 v[174:175], v[232:233], 0, s[36:37]
	s_mov_b32 m0, s62
	s_nop 0
	global_load_lds_dwordx4 v[174:175], off
	s_barrier
; __device__ __forceinline__ unsigned pk2(float lo, float hi) { f32x2 v = {lo, hi}; return __builtin_bit_cast(unsigned, __builtin_convertvector(v, bf16v2)); }
; __device__ __forceinline__ bf16_t f2bf(float f) { return (bf16_t)(pk2(f, 0.f) & 0xffffu); }
;   __device__ __forceinline__ void operator()(const Acc& acc, int brow, int bcol, int wr, int wc, int fr, int fq) const {
;     ...
;         const int r = brow + 128 * ai + 64 * wr + 16 * m + fr;
;         const float rstd = rsqrtf(RS[2 * r + 1] * (1.f / 128.f) + 1e-6f);
;         int b, key; row_bk(r, b, key);
;         bf16_t* krow = Kall + ((size_t)(b * 8) * NKEY + key) * 96 + 4 * fq;
;         bf16_t* vrow = Vt + (size_t)(b * 8) * 64 * NKEY + key + (size_t)(4 * fq) * NKEY;
; #pragma unroll
;         for (int bj = 0; bj < 2; ++bj) {
;           const int cc = bcol - 768 + 128 * bj + 32 * wc, h = cc >> 7, e32 = cc & 127;
; #pragma unroll
;           for (int n = 0; n < 2; ++n) {
;             const f32x4 v = acc[ai][bj][m][n] * rstd;
;             if (e32 < 64) {
;               u32x2 o; o.x = pk2(v[0], v[1]); o.y = pk2(v[2], v[3]);
;               *(u32x2*)(krow + (size_t)h * (NKEY * 96) + e32 + 16 * n) = o;
;             } else {
;               bf16_t* vp = vrow + (size_t)(h * 64 + e32 - 64 + 16 * n) * NKEY;
; #pragma unroll
;               for (int j = 0; j < 4; ++j) vp[(size_t)j * NKEY] = f2bf(v[j]);
	s_waitcnt lgkmcnt(0)
	s_setprio 1
	s_waitcnt lgkmcnt(0)
	v_mfma_f32_16x16x32_bf16 v[60:63], v[148:151], v[180:183], v[60:63]
	v_mfma_f32_16x16x32_bf16 v[56:59], v[156:159], v[180:183], v[56:59]
	v_mfma_f32_16x16x32_bf16 v[44:47], v[148:151], v[188:191], v[44:47]
	v_mfma_f32_16x16x32_bf16 v[40:43], v[156:159], v[188:191], v[40:43]
	v_mfma_f32_16x16x32_bf16 v[28:31], v[148:151], v[196:199], v[28:31]
	v_mfma_f32_16x16x32_bf16 v[24:27], v[156:159], v[196:199], v[24:27]
	v_mfma_f32_16x16x32_bf16 v[12:15], v[148:151], v[204:207], v[12:15]
	v_mfma_f32_16x16x32_bf16 v[8:11], v[156:159], v[204:207], v[8:11]
	v_mfma_f32_16x16x32_bf16 v[60:63], v[152:155], v[184:187], v[60:63]
	v_mfma_f32_16x16x32_bf16 v[56:59], v[160:163], v[184:187], v[56:59]
	v_mfma_f32_16x16x32_bf16 v[44:47], v[152:155], v[192:195], v[44:47]
	v_mfma_f32_16x16x32_bf16 v[40:43], v[160:163], v[192:195], v[40:43]
	v_mfma_f32_16x16x32_bf16 v[28:31], v[152:155], v[200:203], v[28:31]
	v_mfma_f32_16x16x32_bf16 v[24:27], v[160:163], v[200:203], v[24:27]
	v_mfma_f32_16x16x32_bf16 v[12:15], v[152:155], v[208:211], v[12:15]
	v_mfma_f32_16x16x32_bf16 v[8:11], v[160:163], v[208:211], v[8:11]
	s_setprio 0
	s_barrier
	s_add_u32 s2, s10, 0x80080
	s_addc_u32 s3, s11, 0
	s_add_i32 s10, s46, s54
	v_lshl_add_u64 v[148:149], s[2:3], 0, v[128:129]
	s_mov_b32 m0, s10
	s_nop 0
	global_load_lds_dwordx4 v[148:149], off
	v_lshl_add_u64 v[148:149], s[2:3], 0, v[130:131]
	s_add_i32 m0, s10, 0x2000
	s_nop 0
	global_load_lds_dwordx4 v[148:149], off
	s_waitcnt vmcnt(6)
	s_barrier
	s_setprio 1
	v_mfma_f32_16x16x32_bf16 v[52:55], v[212:215], v[180:183], v[52:55]
	v_mfma_f32_16x16x32_bf16 v[48:51], v[220:223], v[180:183], v[48:51]
	v_mfma_f32_16x16x32_bf16 v[36:39], v[212:215], v[188:191], v[36:39]
	v_mfma_f32_16x16x32_bf16 v[32:35], v[220:223], v[188:191], v[32:35]
	v_mfma_f32_16x16x32_bf16 v[20:23], v[212:215], v[196:199], v[20:23]
	v_mfma_f32_16x16x32_bf16 v[16:19], v[220:223], v[196:199], v[16:19]
	v_mfma_f32_16x16x32_bf16 v[4:7], v[212:215], v[204:207], v[4:7]
	v_mfma_f32_16x16x32_bf16 v[0:3], v[220:223], v[204:207], v[0:3]
	v_mfma_f32_16x16x32_bf16 v[52:55], v[216:219], v[184:187], v[52:55]
	v_mfma_f32_16x16x32_bf16 v[48:51], v[224:227], v[184:187], v[48:51]
	v_mfma_f32_16x16x32_bf16 v[36:39], v[216:219], v[192:195], v[36:39]
	v_mfma_f32_16x16x32_bf16 v[32:35], v[224:227], v[192:195], v[32:35]
	v_mfma_f32_16x16x32_bf16 v[20:23], v[216:219], v[200:203], v[20:23]
	v_mfma_f32_16x16x32_bf16 v[16:19], v[224:227], v[200:203], v[16:19]
	v_mfma_f32_16x16x32_bf16 v[4:7], v[216:219], v[208:211], v[4:7]
	v_mfma_f32_16x16x32_bf16 v[0:3], v[224:227], v[208:211], v[0:3]
	s_setprio 0
	s_add_i32 s27, s27, 2
	s_add_u32 s8, s8, 0x100
	s_addc_u32 s9, s9, 0
	s_add_u32 s4, s4, 0x100
	s_addc_u32 s5, s5, 0
	s_cmp_gt_u32 s27, 3
	s_barrier
	s_cbranch_scc0 .LBB0_833
	s_cmp_lt_i32 s30, 0
	s_cbranch_scc0 .LBB0_821
	s_lshl_b32 s4, s13, 8
	s_add_i32 s4, s4, s59
	v_or_b32_e32 v173, s4, v164
	v_lshlrev_b32_e32 v148, 1, v173
	s_lshl_b32 s2, s12, 8
	v_ashrrev_i32_e32 v149, 31, v148
	s_cmp_gt_i32 s12, 2
	v_lshl_add_u64 v[150:151], v[148:149], 2, s[16:17]
	s_mov_b64 s[0:1], -1
	v_cmp_lt_i32_e32 vcc, s67, v173
	s_cbranch_scc0 .LBB0_997
	global_load_dword v152, v[150:151], off offset:4
	global_load_dword v236, v[150:151], off offset:132
	global_load_dword v237, v[150:151], off offset:260
	global_load_dword v238, v[150:151], off offset:388
	global_load_dword v239, v[150:151], off offset:1028
	global_load_dword v240, v[150:151], off offset:1156
	global_load_dword v241, v[150:151], off offset:1284
	global_load_dword v242, v[150:151], off offset:1412
	s_and_saveexec_b64 s[0:1], vcc
	s_xor_b64 s[0:1], exec, s[0:1]
	v_add_u32_e32 v132, 0xfffffc00, v173
	v_lshrrev_b32_e32 v149, 13, v132
	v_and_b32_e32 v132, 0x1fcf, v132
	v_add_u32_e32 v132, 0x100, v132
	s_andn2_saveexec_b64 s[0:1], s[0:1]
	s_ashr_i32 s3, s4, 8
	v_and_b32_e32 v132, 0xcf, v173
	v_mov_b32_e32 v149, s3
	s_or_b64 exec, exec, s[0:1]
	s_waitcnt vmcnt(0)
	v_fmamk_f32 v152, v152, 0x3c000000, v169
	v_mul_f32_e32 v153, 0x4b800000, v152
	v_cmp_gt_f32_e32 vcc, s68, v152
	v_lshlrev_b32_e32 v149, 3, v149
	s_add_i32 s5, s2, 0xfffffd00
	v_cndmask_b32_e32 v152, v152, v153, vcc
	v_rsq_f32_e32 v152, v152
	s_lshr_b32 s3, s5, 1
	s_add_i32 s3, s3, s64
	v_mul_f32_e32 v153, 0x45800000, v152
	v_cndmask_b32_e32 v154, v152, v153, vcc
	v_mov_b64_e32 v[152:153], s[34:35]
	v_mad_i64_i32 v[152:153], s[0:1], v149, s71, v[152:153]
	v_lshl_add_u64 v[152:153], v[132:133], 1, v[152:153]
	v_lshl_add_u64 v[152:153], v[152:153], 0, v[134:135]
	v_pk_mul_f32 v[160:161], v[126:127], v[154:155] op_sel_hi:[1,0]
	v_pk_mul_f32 v[162:163], v[124:125], v[154:155] op_sel_hi:[1,0]
	s_mov_b64 s[0:1], -1
	s_and_b64 vcc, exec, s[38:39]
	s_cbranch_vccz .LBB0_842
	v_mad_u64_u32 v[156:157], s[0:1], s3, v170, v[152:153]
	v_add_co_u32_e32 v158, vcc, 0x4000, v156
	s_nop 0
	v_cvt_pk_bf16_f32 v155, v162, s0
	global_store_short v[156:157], v155, off
	v_cvt_pk_bf16_f32 v155, v163, s0
	v_addc_co_u32_e32 v159, vcc, 0, v157, vcc
	global_store_short v[158:159], v155, off offset:512
	v_add_co_u32_e32 v158, vcc, 0x8000, v156
	v_cvt_pk_bf16_f32 v155, v160, s0
	s_nop 0
	v_addc_co_u32_e32 v159, vcc, 0, v157, vcc
	v_add_co_u32_e32 v156, vcc, 0xc000, v156
	global_store_short v[158:159], v155, off offset:1024
	v_cvt_pk_bf16_f32 v155, v161, s0
	v_addc_co_u32_e32 v157, vcc, 0, v157, vcc
	global_store_short v[156:157], v155, off offset:1536
	s_mov_b64 s[0:1], 0

; __device__ __forceinline__ unsigned pk2(float lo, float hi) { f32x2 v = {lo, hi}; return __builtin_bit_cast(unsigned, __builtin_convertvector(v, bf16v2)); }
; __device__ __forceinline__ bf16_t f2bf(float f) { return (bf16_t)(pk2(f, 0.f) & 0xffffu); }
;   __device__ __forceinline__ void operator()(const Acc& acc, int brow, int bcol, int wr, int wc, int fr, int fq) const {
;     ...
;         const int r = brow + 128 * ai + 64 * wr + 16 * m + fr;
;         const float rstd = rsqrtf(RS[2 * r + 1] * (1.f / 128.f) + 1e-6f);
;         int b, key; row_bk(r, b, key);
;         bf16_t* krow = Kall + ((size_t)(b * 8) * NKEY + key) * 96 + 4 * fq;
;         bf16_t* vrow = Vt + (size_t)(b * 8) * 64 * NKEY + key + (size_t)(4 * fq) * NKEY;
; #pragma unroll
;         for (int bj = 0; bj < 2; ++bj) {
;           const int cc = bcol - 768 + 128 * bj + 32 * wc, h = cc >> 7, e32 = cc & 127;
; #pragma unroll
;           for (int n = 0; n < 2; ++n) {
;             const f32x4 v = acc[ai][bj][m][n] * rstd;
;             if (e32 < 64) {
;               u32x2 o; o.x = pk2(v[0], v[1]); o.y = pk2(v[2], v[3]);
;               *(u32x2*)(krow + (size_t)h * (NKEY * 96) + e32 + 16 * n) = o;
;             } else {
;               bf16_t* vp = vrow + (size_t)(h * 64 + e32 - 64 + 16 * n) * NKEY;
; #pragma unroll
;               for (int j = 0; j < 4; ++j) vp[(size_t)j * NKEY] = f2bf(v[j]);
.LBB0_856:
	v_or_b32_e32 v153, 16, v173
	v_lshlrev_b32_e32 v154, 1, v153
	v_ashrrev_i32_e32 v155, 31, v154
	v_lshl_add_u64 v[154:155], v[154:155], 2, s[16:17]
	v_mov_b32_e32 v149, v236
	v_cmp_lt_i32_e32 vcc, s67, v153
	s_and_saveexec_b64 s[0:1], vcc
	s_xor_b64 s[0:1], exec, s[0:1]
	v_add_u32_e32 v132, 0xfffffc10, v173
	v_lshrrev_b32_e32 v152, 13, v132
	v_and_b32_e32 v132, 0x1fdf, v132
	v_add_u32_e32 v132, 0x100, v132
	s_andn2_saveexec_b64 s[0:1], s[0:1]
	s_ashr_i32 s11, s4, 8
	v_and_b32_e32 v132, 0xdf, v153
	v_mov_b32_e32 v152, s11
	s_or_b64 exec, exec, s[0:1]
	v_fmamk_f32 v149, v149, 0x3c000000, v169
	v_mul_f32_e32 v153, 0x4b800000, v149
	v_cmp_gt_f32_e32 vcc, s68, v149
	s_nop 1
	v_cndmask_b32_e32 v149, v149, v153, vcc
	v_rsq_f32_e32 v154, v149
	v_lshlrev_b32_e32 v149, 3, v152
	v_mov_b64_e32 v[152:153], s[34:35]
	v_mad_i64_i32 v[152:153], s[0:1], v149, s71, v[152:153]
	v_mul_f32_e32 v155, 0x45800000, v154
	v_cndmask_b32_e32 v154, v154, v155, vcc
	v_lshl_add_u64 v[152:153], v[132:133], 1, v[152:153]
	v_lshl_add_u64 v[152:153], v[152:153], 0, v[134:135]
	v_pk_mul_f32 v[160:161], v[110:111], v[154:155] op_sel_hi:[1,0]
	v_pk_mul_f32 v[162:163], v[108:109], v[154:155] op_sel_hi:[1,0]
	s_and_b64 vcc, exec, s[8:9]
	s_mov_b64 s[0:1], -1
	s_cbranch_vccnz .LBB0_862
	v_mad_u64_u32 v[156:157], s[0:1], s3, v170, v[152:153]
	v_add_co_u32_e32 v158, vcc, 0x4000, v156
	s_nop 0
	v_cvt_pk_bf16_f32 v155, v162, s0
	global_store_short v[156:157], v155, off
	v_cvt_pk_bf16_f32 v155, v163, s0
	v_addc_co_u32_e32 v159, vcc, 0, v157, vcc
	global_store_short v[158:159], v155, off offset:512
	v_add_co_u32_e32 v158, vcc, 0x8000, v156
	v_cvt_pk_bf16_f32 v155, v160, s0
	s_nop 0
	v_addc_co_u32_e32 v159, vcc, 0, v157, vcc
	v_add_co_u32_e32 v156, vcc, 0xc000, v156
	global_store_short v[158:159], v155, off offset:1024
	v_cvt_pk_bf16_f32 v155, v161, s0
	v_addc_co_u32_e32 v157, vcc, 0, v157, vcc
	s_mov_b64 s[0:1], 0
	global_store_short v[156:157], v155, off offset:1536

; __device__ __forceinline__ unsigned pk2(float lo, float hi) { f32x2 v = {lo, hi}; return __builtin_bit_cast(unsigned, __builtin_convertvector(v, bf16v2)); }
; __device__ __forceinline__ bf16_t f2bf(float f) { return (bf16_t)(pk2(f, 0.f) & 0xffffu); }
;   __device__ __forceinline__ void operator()(const Acc& acc, int brow, int bcol, int wr, int wc, int fr, int fq) const {
;     ...
;         const int r = brow + 128 * ai + 64 * wr + 16 * m + fr;
;         const float rstd = rsqrtf(RS[2 * r + 1] * (1.f / 128.f) + 1e-6f);
;         int b, key; row_bk(r, b, key);
;         bf16_t* krow = Kall + ((size_t)(b * 8) * NKEY + key) * 96 + 4 * fq;
;         bf16_t* vrow = Vt + (size_t)(b * 8) * 64 * NKEY + key + (size_t)(4 * fq) * NKEY;
; #pragma unroll
;         for (int bj = 0; bj < 2; ++bj) {
;           const int cc = bcol - 768 + 128 * bj + 32 * wc, h = cc >> 7, e32 = cc & 127;
; #pragma unroll
;           for (int n = 0; n < 2; ++n) {
;             const f32x4 v = acc[ai][bj][m][n] * rstd;
;             if (e32 < 64) {
;               u32x2 o; o.x = pk2(v[0], v[1]); o.y = pk2(v[2], v[3]);
;               *(u32x2*)(krow + (size_t)h * (NKEY * 96) + e32 + 16 * n) = o;
;             } else {
;               bf16_t* vp = vrow + (size_t)(h * 64 + e32 - 64 + 16 * n) * NKEY;
; #pragma unroll
;               for (int j = 0; j < 4; ++j) vp[(size_t)j * NKEY] = f2bf(v[j]);
.LBB0_876:
	v_or_b32_e32 v153, 32, v173
	v_lshlrev_b32_e32 v154, 1, v153
	v_ashrrev_i32_e32 v155, 31, v154
	v_lshl_add_u64 v[154:155], v[154:155], 2, s[16:17]
	v_mov_b32_e32 v149, v237
	v_cmp_lt_i32_e32 vcc, s67, v153
	s_and_saveexec_b64 s[0:1], vcc
	s_xor_b64 s[0:1], exec, s[0:1]
	v_add_u32_e32 v132, 0xfffffc20, v173
	v_lshrrev_b32_e32 v152, 13, v132
	v_and_b32_e32 v132, 0x1fef, v132
	v_add_u32_e32 v132, 0x100, v132
	s_andn2_saveexec_b64 s[0:1], s[0:1]
	s_ashr_i32 s27, s4, 8
	v_and_b32_e32 v132, 0xef, v153
	v_mov_b32_e32 v152, s27
	s_or_b64 exec, exec, s[0:1]
	v_fmamk_f32 v149, v149, 0x3c000000, v169
	v_mul_f32_e32 v153, 0x4b800000, v149
	v_cmp_gt_f32_e32 vcc, s68, v149
	s_nop 1
	v_cndmask_b32_e32 v149, v149, v153, vcc
	v_rsq_f32_e32 v154, v149
	v_lshlrev_b32_e32 v149, 3, v152
	v_mov_b64_e32 v[152:153], s[34:35]
	v_mad_i64_i32 v[152:153], s[0:1], v149, s71, v[152:153]
	v_mul_f32_e32 v155, 0x45800000, v154
	v_cndmask_b32_e32 v154, v154, v155, vcc
	v_lshl_add_u64 v[152:153], v[132:133], 1, v[152:153]
	v_lshl_add_u64 v[152:153], v[152:153], 0, v[134:135]
	v_pk_mul_f32 v[160:161], v[94:95], v[154:155] op_sel_hi:[1,0]
	v_pk_mul_f32 v[162:163], v[92:93], v[154:155] op_sel_hi:[1,0]
	s_and_b64 vcc, exec, s[8:9]
	s_mov_b64 s[0:1], -1
	s_cbranch_vccnz .LBB0_882
	v_mad_u64_u32 v[156:157], s[0:1], s3, v170, v[152:153]
	v_add_co_u32_e32 v158, vcc, 0x4000, v156
	s_nop 0
	v_cvt_pk_bf16_f32 v155, v162, s0
	global_store_short v[156:157], v155, off
	v_cvt_pk_bf16_f32 v155, v163, s0
	v_addc_co_u32_e32 v159, vcc, 0, v157, vcc
	global_store_short v[158:159], v155, off offset:512
	v_add_co_u32_e32 v158, vcc, 0x8000, v156
	v_cvt_pk_bf16_f32 v155, v160, s0
	s_nop 0
	v_addc_co_u32_e32 v159, vcc, 0, v157, vcc
	v_add_co_u32_e32 v156, vcc, 0xc000, v156
	global_store_short v[158:159], v155, off offset:1024
	v_cvt_pk_bf16_f32 v155, v161, s0
	v_addc_co_u32_e32 v157, vcc, 0, v157, vcc
	s_mov_b64 s[0:1], 0
	global_store_short v[156:157], v155, off offset:1536

; __device__ __forceinline__ unsigned pk2(float lo, float hi) { f32x2 v = {lo, hi}; return __builtin_bit_cast(unsigned, __builtin_convertvector(v, bf16v2)); }
; __device__ __forceinline__ bf16_t f2bf(float f) { return (bf16_t)(pk2(f, 0.f) & 0xffffu); }
;   __device__ __forceinline__ void operator()(const Acc& acc, int brow, int bcol, int wr, int wc, int fr, int fq) const {
;     ...
;         const int r = brow + 128 * ai + 64 * wr + 16 * m + fr;
;         const float rstd = rsqrtf(RS[2 * r + 1] * (1.f / 128.f) + 1e-6f);
;         int b, key; row_bk(r, b, key);
;         bf16_t* krow = Kall + ((size_t)(b * 8) * NKEY + key) * 96 + 4 * fq;
;         bf16_t* vrow = Vt + (size_t)(b * 8) * 64 * NKEY + key + (size_t)(4 * fq) * NKEY;
; #pragma unroll
;         for (int bj = 0; bj < 2; ++bj) {
;           const int cc = bcol - 768 + 128 * bj + 32 * wc, h = cc >> 7, e32 = cc & 127;
; #pragma unroll
;           for (int n = 0; n < 2; ++n) {
;             const f32x4 v = acc[ai][bj][m][n] * rstd;
;             if (e32 < 64) {
;               u32x2 o; o.x = pk2(v[0], v[1]); o.y = pk2(v[2], v[3]);
;               *(u32x2*)(krow + (size_t)h * (NKEY * 96) + e32 + 16 * n) = o;
;             } else {
;               bf16_t* vp = vrow + (size_t)(h * 64 + e32 - 64 + 16 * n) * NKEY;
; #pragma unroll
;               for (int j = 0; j < 4; ++j) vp[(size_t)j * NKEY] = f2bf(v[j]);
.LBB0_896:
	v_or_b32_e32 v153, 48, v173
	v_lshlrev_b32_e32 v154, 1, v153
	v_ashrrev_i32_e32 v155, 31, v154
	v_lshl_add_u64 v[154:155], v[154:155], 2, s[16:17]
	v_mov_b32_e32 v149, v238
	v_cmp_lt_i32_e32 vcc, s67, v153
	s_and_saveexec_b64 s[0:1], vcc
	s_xor_b64 s[0:1], exec, s[0:1]
	v_add_u32_e32 v132, 0xfffffc30, v173
	v_lshrrev_b32_e32 v152, 13, v132
	v_and_b32_e32 v132, 0x1fff, v132
	v_add_u32_e32 v132, 0x100, v132
	s_andn2_saveexec_b64 s[0:1], s[0:1]
	s_ashr_i32 s27, s4, 8
	v_and_b32_e32 v132, 0xff, v153
	v_mov_b32_e32 v152, s27
	s_or_b64 exec, exec, s[0:1]
	v_fmamk_f32 v149, v149, 0x3c000000, v169
	v_mul_f32_e32 v153, 0x4b800000, v149
	v_cmp_gt_f32_e32 vcc, s68, v149
	s_nop 1
	v_cndmask_b32_e32 v149, v149, v153, vcc
	v_rsq_f32_e32 v154, v149
	v_lshlrev_b32_e32 v149, 3, v152
	v_mov_b64_e32 v[152:153], s[34:35]
	v_mad_i64_i32 v[152:153], s[0:1], v149, s71, v[152:153]
	v_mul_f32_e32 v155, 0x45800000, v154
	v_cndmask_b32_e32 v154, v154, v155, vcc
	v_lshl_add_u64 v[152:153], v[132:133], 1, v[152:153]
	v_lshl_add_u64 v[152:153], v[152:153], 0, v[134:135]
	v_pk_mul_f32 v[160:161], v[78:79], v[154:155] op_sel_hi:[1,0]
	v_pk_mul_f32 v[162:163], v[76:77], v[154:155] op_sel_hi:[1,0]
	s_and_b64 vcc, exec, s[8:9]
	s_mov_b64 s[0:1], -1
	s_cbranch_vccnz .LBB0_902
	v_mad_u64_u32 v[156:157], s[0:1], s3, v170, v[152:153]
	v_add_co_u32_e32 v158, vcc, 0x4000, v156
	s_nop 0
	v_cvt_pk_bf16_f32 v155, v162, s0
	global_store_short v[156:157], v155, off
	v_cvt_pk_bf16_f32 v155, v163, s0
	v_addc_co_u32_e32 v159, vcc, 0, v157, vcc
	global_store_short v[158:159], v155, off offset:512
	v_add_co_u32_e32 v158, vcc, 0x8000, v156
	v_cvt_pk_bf16_f32 v155, v160, s0
	s_nop 0
	v_addc_co_u32_e32 v159, vcc, 0, v157, vcc
	v_add_co_u32_e32 v156, vcc, 0xc000, v156
	global_store_short v[158:159], v155, off offset:1024
	v_cvt_pk_bf16_f32 v155, v161, s0
	v_addc_co_u32_e32 v157, vcc, 0, v157, vcc
	s_mov_b64 s[0:1], 0
	global_store_short v[156:157], v155, off offset:1536

; __device__ __forceinline__ unsigned pk2(float lo, float hi) { f32x2 v = {lo, hi}; return __builtin_bit_cast(unsigned, __builtin_convertvector(v, bf16v2)); }
; __device__ __forceinline__ bf16_t f2bf(float f) { return (bf16_t)(pk2(f, 0.f) & 0xffffu); }
;   __device__ __forceinline__ void operator()(const Acc& acc, int brow, int bcol, int wr, int wc, int fr, int fq) const {
;     ...
;         const int r = brow + 128 * ai + 64 * wr + 16 * m + fr;
;         const float rstd = rsqrtf(RS[2 * r + 1] * (1.f / 128.f) + 1e-6f);
;         int b, key; row_bk(r, b, key);
;         bf16_t* krow = Kall + ((size_t)(b * 8) * NKEY + key) * 96 + 4 * fq;
;         bf16_t* vrow = Vt + (size_t)(b * 8) * 64 * NKEY + key + (size_t)(4 * fq) * NKEY;
; #pragma unroll
;         for (int bj = 0; bj < 2; ++bj) {
;           const int cc = bcol - 768 + 128 * bj + 32 * wc, h = cc >> 7, e32 = cc & 127;
; #pragma unroll
;           for (int n = 0; n < 2; ++n) {
;             const f32x4 v = acc[ai][bj][m][n] * rstd;
;             if (e32 < 64) {
;               u32x2 o; o.x = pk2(v[0], v[1]); o.y = pk2(v[2], v[3]);
;               *(u32x2*)(krow + (size_t)h * (NKEY * 96) + e32 + 16 * n) = o;
;             } else {
;               bf16_t* vp = vrow + (size_t)(h * 64 + e32 - 64 + 16 * n) * NKEY;
; #pragma unroll
;               for (int j = 0; j < 4; ++j) vp[(size_t)j * NKEY] = f2bf(v[j]);
.LBB0_916:
	v_add_u32_e32 v153, 0x80, v173
	v_lshlrev_b32_e32 v154, 1, v153
	v_ashrrev_i32_e32 v155, 31, v154
	v_lshl_add_u64 v[154:155], v[154:155], 2, s[16:17]
	v_mov_b32_e32 v152, v239
	v_cmp_lt_i32_e32 vcc, s67, v153
	s_and_saveexec_b64 s[0:1], vcc
	s_xor_b64 s[0:1], exec, s[0:1]
	v_add_u32_e32 v132, 0xfffffc80, v173
	v_lshrrev_b32_e32 v149, 13, v132
	v_and_b32_e32 v132, 0x1fcf, v132
	v_add_u32_e32 v132, 0x100, v132
	s_andn2_saveexec_b64 s[0:1], s[0:1]
	v_ashrrev_i32_e32 v149, 8, v153
	v_and_b32_e32 v132, 0xcf, v153
	s_or_b64 exec, exec, s[0:1]
	v_fmamk_f32 v152, v152, 0x3c000000, v169
	v_mul_f32_e32 v153, 0x4b800000, v152
	v_cmp_gt_f32_e32 vcc, s68, v152
	v_lshlrev_b32_e32 v149, 3, v149
	s_nop 0
	v_cndmask_b32_e32 v152, v152, v153, vcc
	v_rsq_f32_e32 v154, v152
	v_mov_b64_e32 v[152:153], s[34:35]
	v_mad_i64_i32 v[152:153], s[0:1], v149, s71, v[152:153]
	v_mul_f32_e32 v155, 0x45800000, v154
	v_cndmask_b32_e32 v154, v154, v155, vcc
	v_lshl_add_u64 v[152:153], v[132:133], 1, v[152:153]
	v_lshl_add_u64 v[152:153], v[152:153], 0, v[134:135]
	v_pk_mul_f32 v[160:161], v[62:63], v[154:155] op_sel_hi:[1,0]
	v_pk_mul_f32 v[162:163], v[60:61], v[154:155] op_sel_hi:[1,0]
	s_and_b64 vcc, exec, s[8:9]
	s_mov_b64 s[0:1], -1
	s_cbranch_vccnz .LBB0_922
	v_mad_u64_u32 v[156:157], s[0:1], s3, v170, v[152:153]
	v_add_co_u32_e32 v158, vcc, 0x4000, v156
	s_nop 0
	v_cvt_pk_bf16_f32 v155, v162, s0
	global_store_short v[156:157], v155, off
	v_cvt_pk_bf16_f32 v155, v163, s0
	v_addc_co_u32_e32 v159, vcc, 0, v157, vcc
	global_store_short v[158:159], v155, off offset:512
	v_add_co_u32_e32 v158, vcc, 0x8000, v156
	v_cvt_pk_bf16_f32 v155, v160, s0
	s_nop 0
	v_addc_co_u32_e32 v159, vcc, 0, v157, vcc
	v_add_co_u32_e32 v156, vcc, 0xc000, v156
	global_store_short v[158:159], v155, off offset:1024
	v_cvt_pk_bf16_f32 v155, v161, s0
	v_addc_co_u32_e32 v157, vcc, 0, v157, vcc
	s_mov_b64 s[0:1], 0
	global_store_short v[156:157], v155, off offset:1536

; __device__ __forceinline__ unsigned pk2(float lo, float hi) { f32x2 v = {lo, hi}; return __builtin_bit_cast(unsigned, __builtin_convertvector(v, bf16v2)); }
; __device__ __forceinline__ bf16_t f2bf(float f) { return (bf16_t)(pk2(f, 0.f) & 0xffffu); }
;   __device__ __forceinline__ void operator()(const Acc& acc, int brow, int bcol, int wr, int wc, int fr, int fq) const {
;     ...
;         const int r = brow + 128 * ai + 64 * wr + 16 * m + fr;
;         const float rstd = rsqrtf(RS[2 * r + 1] * (1.f / 128.f) + 1e-6f);
;         int b, key; row_bk(r, b, key);
;         bf16_t* krow = Kall + ((size_t)(b * 8) * NKEY + key) * 96 + 4 * fq;
;         bf16_t* vrow = Vt + (size_t)(b * 8) * 64 * NKEY + key + (size_t)(4 * fq) * NKEY;
; #pragma unroll
;         for (int bj = 0; bj < 2; ++bj) {
;           const int cc = bcol - 768 + 128 * bj + 32 * wc, h = cc >> 7, e32 = cc & 127;
; #pragma unroll
;           for (int n = 0; n < 2; ++n) {
;             const f32x4 v = acc[ai][bj][m][n] * rstd;
;             if (e32 < 64) {
;               u32x2 o; o.x = pk2(v[0], v[1]); o.y = pk2(v[2], v[3]);
;               *(u32x2*)(krow + (size_t)h * (NKEY * 96) + e32 + 16 * n) = o;
;             } else {
;               bf16_t* vp = vrow + (size_t)(h * 64 + e32 - 64 + 16 * n) * NKEY;
; #pragma unroll
;               for (int j = 0; j < 4; ++j) vp[(size_t)j * NKEY] = f2bf(v[j]);
.LBB0_936:
	v_add_u32_e32 v153, 0x90, v173
	v_lshlrev_b32_e32 v154, 1, v153
	v_ashrrev_i32_e32 v155, 31, v154
	v_lshl_add_u64 v[154:155], v[154:155], 2, s[16:17]
	v_mov_b32_e32 v152, v240
	v_cmp_lt_i32_e32 vcc, s67, v153
	s_and_saveexec_b64 s[0:1], vcc
	s_xor_b64 s[0:1], exec, s[0:1]
	v_add_u32_e32 v132, 0xfffffc90, v173
	v_lshrrev_b32_e32 v149, 13, v132
	v_and_b32_e32 v132, 0x1fdf, v132
	v_add_u32_e32 v132, 0x100, v132
	s_andn2_saveexec_b64 s[0:1], s[0:1]
	v_ashrrev_i32_e32 v149, 8, v153
	v_and_b32_e32 v132, 0xdf, v153
	s_or_b64 exec, exec, s[0:1]
	v_fmamk_f32 v152, v152, 0x3c000000, v169
	v_mul_f32_e32 v153, 0x4b800000, v152
	v_cmp_gt_f32_e32 vcc, s68, v152
	v_lshlrev_b32_e32 v149, 3, v149
	s_nop 0
	v_cndmask_b32_e32 v152, v152, v153, vcc
	v_rsq_f32_e32 v154, v152
	v_mov_b64_e32 v[152:153], s[34:35]
	v_mad_i64_i32 v[152:153], s[0:1], v149, s71, v[152:153]
	v_mul_f32_e32 v155, 0x45800000, v154
	v_cndmask_b32_e32 v154, v154, v155, vcc
	v_lshl_add_u64 v[152:153], v[132:133], 1, v[152:153]
	v_lshl_add_u64 v[152:153], v[152:153], 0, v[134:135]
	v_pk_mul_f32 v[160:161], v[46:47], v[154:155] op_sel_hi:[1,0]
	v_pk_mul_f32 v[162:163], v[44:45], v[154:155] op_sel_hi:[1,0]
	s_and_b64 vcc, exec, s[8:9]
	s_mov_b64 s[0:1], -1
	s_cbranch_vccnz .LBB0_942
	v_mad_u64_u32 v[156:157], s[0:1], s3, v170, v[152:153]
	v_add_co_u32_e32 v158, vcc, 0x4000, v156
	s_nop 0
	v_cvt_pk_bf16_f32 v155, v162, s0
	global_store_short v[156:157], v155, off
	v_cvt_pk_bf16_f32 v155, v163, s0
	v_addc_co_u32_e32 v159, vcc, 0, v157, vcc
	global_store_short v[158:159], v155, off offset:512
	v_add_co_u32_e32 v158, vcc, 0x8000, v156
	v_cvt_pk_bf16_f32 v155, v160, s0
	s_nop 0
	v_addc_co_u32_e32 v159, vcc, 0, v157, vcc
	v_add_co_u32_e32 v156, vcc, 0xc000, v156
	global_store_short v[158:159], v155, off offset:1024
	v_cvt_pk_bf16_f32 v155, v161, s0
	v_addc_co_u32_e32 v157, vcc, 0, v157, vcc
	s_mov_b64 s[0:1], 0
	global_store_short v[156:157], v155, off offset:1536

; __device__ __forceinline__ unsigned pk2(float lo, float hi) { f32x2 v = {lo, hi}; return __builtin_bit_cast(unsigned, __builtin_convertvector(v, bf16v2)); }
; __device__ __forceinline__ bf16_t f2bf(float f) { return (bf16_t)(pk2(f, 0.f) & 0xffffu); }
;   __device__ __forceinline__ void operator()(const Acc& acc, int brow, int bcol, int wr, int wc, int fr, int fq) const {
;     ...
;         const int r = brow + 128 * ai + 64 * wr + 16 * m + fr;
;         const float rstd = rsqrtf(RS[2 * r + 1] * (1.f / 128.f) + 1e-6f);
;         int b, key; row_bk(r, b, key);
;         bf16_t* krow = Kall + ((size_t)(b * 8) * NKEY + key) * 96 + 4 * fq;
;         bf16_t* vrow = Vt + (size_t)(b * 8) * 64 * NKEY + key + (size_t)(4 * fq) * NKEY;
; #pragma unroll
;         for (int bj = 0; bj < 2; ++bj) {
;           const int cc = bcol - 768 + 128 * bj + 32 * wc, h = cc >> 7, e32 = cc & 127;
; #pragma unroll
;           for (int n = 0; n < 2; ++n) {
;             const f32x4 v = acc[ai][bj][m][n] * rstd;
;             if (e32 < 64) {
;               u32x2 o; o.x = pk2(v[0], v[1]); o.y = pk2(v[2], v[3]);
;               *(u32x2*)(krow + (size_t)h * (NKEY * 96) + e32 + 16 * n) = o;
;             } else {
;               bf16_t* vp = vrow + (size_t)(h * 64 + e32 - 64 + 16 * n) * NKEY;
; #pragma unroll
;               for (int j = 0; j < 4; ++j) vp[(size_t)j * NKEY] = f2bf(v[j]);
.LBB0_956:
	v_add_u32_e32 v153, 0xa0, v173
	v_lshlrev_b32_e32 v154, 1, v153
	v_ashrrev_i32_e32 v155, 31, v154
	v_lshl_add_u64 v[154:155], v[154:155], 2, s[16:17]
	v_mov_b32_e32 v152, v241
	v_cmp_lt_i32_e32 vcc, s67, v153
	s_and_saveexec_b64 s[0:1], vcc
	s_xor_b64 s[0:1], exec, s[0:1]
	v_add_u32_e32 v132, 0xfffffca0, v173
	v_lshrrev_b32_e32 v149, 13, v132
	v_and_b32_e32 v132, 0x1fef, v132
	v_add_u32_e32 v132, 0x100, v132
	s_andn2_saveexec_b64 s[0:1], s[0:1]
	v_ashrrev_i32_e32 v149, 8, v153
	v_and_b32_e32 v132, 0xef, v153
	s_or_b64 exec, exec, s[0:1]
	v_fmamk_f32 v152, v152, 0x3c000000, v169
	v_mul_f32_e32 v153, 0x4b800000, v152
	v_cmp_gt_f32_e32 vcc, s68, v152
	v_lshlrev_b32_e32 v149, 3, v149
	s_nop 0
	v_cndmask_b32_e32 v152, v152, v153, vcc
	v_rsq_f32_e32 v154, v152
	v_mov_b64_e32 v[152:153], s[34:35]
	v_mad_i64_i32 v[152:153], s[0:1], v149, s71, v[152:153]
	v_mul_f32_e32 v155, 0x45800000, v154
	v_cndmask_b32_e32 v154, v154, v155, vcc
	v_lshl_add_u64 v[152:153], v[132:133], 1, v[152:153]
	v_lshl_add_u64 v[152:153], v[152:153], 0, v[134:135]
	v_pk_mul_f32 v[160:161], v[30:31], v[154:155] op_sel_hi:[1,0]
	v_pk_mul_f32 v[162:163], v[28:29], v[154:155] op_sel_hi:[1,0]
	s_and_b64 vcc, exec, s[8:9]
	s_mov_b64 s[0:1], -1
	s_cbranch_vccnz .LBB0_962
	v_mad_u64_u32 v[156:157], s[0:1], s3, v170, v[152:153]
	v_add_co_u32_e32 v158, vcc, 0x4000, v156
	s_nop 0
	v_cvt_pk_bf16_f32 v155, v162, s0
	global_store_short v[156:157], v155, off
	v_cvt_pk_bf16_f32 v155, v163, s0
	v_addc_co_u32_e32 v159, vcc, 0, v157, vcc
	global_store_short v[158:159], v155, off offset:512
	v_add_co_u32_e32 v158, vcc, 0x8000, v156
	v_cvt_pk_bf16_f32 v155, v160, s0
	s_nop 0
	v_addc_co_u32_e32 v159, vcc, 0, v157, vcc
	v_add_co_u32_e32 v156, vcc, 0xc000, v156
	global_store_short v[158:159], v155, off offset:1024
	v_cvt_pk_bf16_f32 v155, v161, s0
	v_addc_co_u32_e32 v157, vcc, 0, v157, vcc
	s_mov_b64 s[0:1], 0
	global_store_short v[156:157], v155, off offset:1536

; __device__ __forceinline__ unsigned pk2(float lo, float hi) { f32x2 v = {lo, hi}; return __builtin_bit_cast(unsigned, __builtin_convertvector(v, bf16v2)); }
; __device__ __forceinline__ bf16_t f2bf(float f) { return (bf16_t)(pk2(f, 0.f) & 0xffffu); }
;   __device__ __forceinline__ void operator()(const Acc& acc, int brow, int bcol, int wr, int wc, int fr, int fq) const {
;     ...
;         const int r = brow + 128 * ai + 64 * wr + 16 * m + fr;
;         const float rstd = rsqrtf(RS[2 * r + 1] * (1.f / 128.f) + 1e-6f);
;         int b, key; row_bk(r, b, key);
;         bf16_t* krow = Kall + ((size_t)(b * 8) * NKEY + key) * 96 + 4 * fq;
;         bf16_t* vrow = Vt + (size_t)(b * 8) * 64 * NKEY + key + (size_t)(4 * fq) * NKEY;
; #pragma unroll
;         for (int bj = 0; bj < 2; ++bj) {
;           const int cc = bcol - 768 + 128 * bj + 32 * wc, h = cc >> 7, e32 = cc & 127;
; #pragma unroll
;           for (int n = 0; n < 2; ++n) {
;             const f32x4 v = acc[ai][bj][m][n] * rstd;
;             if (e32 < 64) {
;               u32x2 o; o.x = pk2(v[0], v[1]); o.y = pk2(v[2], v[3]);
;               *(u32x2*)(krow + (size_t)h * (NKEY * 96) + e32 + 16 * n) = o;
;             } else {
;               bf16_t* vp = vrow + (size_t)(h * 64 + e32 - 64 + 16 * n) * NKEY;
; #pragma unroll
;               for (int j = 0; j < 4; ++j) vp[(size_t)j * NKEY] = f2bf(v[j]);
.LBB0_976:
	v_add_u32_e32 v153, 0xb0, v173
	v_lshlrev_b32_e32 v154, 1, v153
	v_ashrrev_i32_e32 v155, 31, v154
	v_lshl_add_u64 v[154:155], v[154:155], 2, s[16:17]
	v_mov_b32_e32 v152, v242
	v_cmp_lt_i32_e32 vcc, s67, v153
	s_and_saveexec_b64 s[0:1], vcc
	s_xor_b64 s[0:1], exec, s[0:1]
	v_add_u32_e32 v132, 0xfffffcb0, v173
	v_lshrrev_b32_e32 v149, 13, v132
	v_and_b32_e32 v132, 0x1fff, v132
	v_add_u32_e32 v132, 0x100, v132
	s_andn2_saveexec_b64 s[0:1], s[0:1]
	v_ashrrev_i32_e32 v149, 8, v153
	v_and_b32_e32 v132, 0xff, v153
	s_or_b64 exec, exec, s[0:1]
	v_fmamk_f32 v152, v152, 0x3c000000, v169
	v_mul_f32_e32 v153, 0x4b800000, v152
	v_cmp_gt_f32_e32 vcc, s68, v152
	v_lshlrev_b32_e32 v149, 3, v149
	s_nop 0
	v_cndmask_b32_e32 v152, v152, v153, vcc
	v_rsq_f32_e32 v154, v152
	v_mov_b64_e32 v[152:153], s[34:35]
	v_mad_i64_i32 v[152:153], s[0:1], v149, s71, v[152:153]
	v_mul_f32_e32 v155, 0x45800000, v154
	v_cndmask_b32_e32 v154, v154, v155, vcc
	v_lshl_add_u64 v[152:153], v[132:133], 1, v[152:153]
	v_lshl_add_u64 v[152:153], v[152:153], 0, v[134:135]
	v_pk_mul_f32 v[160:161], v[14:15], v[154:155] op_sel_hi:[1,0]
	v_pk_mul_f32 v[162:163], v[12:13], v[154:155] op_sel_hi:[1,0]
	s_and_b64 vcc, exec, s[8:9]
	s_mov_b64 s[0:1], -1
	s_cbranch_vccnz .LBB0_982
	v_mad_u64_u32 v[156:157], s[0:1], s3, v170, v[152:153]
	v_add_co_u32_e32 v158, vcc, 0x4000, v156
	s_nop 0
	v_cvt_pk_bf16_f32 v155, v162, s0
	global_store_short v[156:157], v155, off
	v_cvt_pk_bf16_f32 v155, v163, s0
	v_addc_co_u32_e32 v159, vcc, 0, v157, vcc
	global_store_short v[158:159], v155, off offset:512
	v_add_co_u32_e32 v158, vcc, 0x8000, v156
	v_cvt_pk_bf16_f32 v155, v160, s0
	s_nop 0
	v_addc_co_u32_e32 v159, vcc, 0, v157, vcc
	v_add_co_u32_e32 v156, vcc, 0xc000, v156
	global_store_short v[158:159], v155, off offset:1024
	v_cvt_pk_bf16_f32 v155, v161, s0
	v_addc_co_u32_e32 v157, vcc, 0, v157, vcc
	s_mov_b64 s[0:1], 0
	global_store_short v[156:157], v155, off offset:1536
